# B-branch segment combine loop: all seven loads of an iteration issued together at the top (one exposed memory round trip per iteration instead of three)
# speedup vs baseline: 1.0026x; 1.0004x over previous
; __device__ __forceinline__ int otid() { int t = __builtin_amdgcn_workitem_id_x(); asm volatile("" : "+v"(t)); return t; }
; __device__ __forceinline__ int obid() { int t = __builtin_amdgcn_workgroup_id_x(); asm volatile("" : "+s"(t)); return t; }
; __device__ __forceinline__ u32x4 pack8(const float (&f)[8]) { u32x4 w; w.x = pk2(f[0], f[1]); w.y = pk2(f[2], f[3]); w.z = pk2(f[4], f[5]); w.w = pk2(f[6], f[7]); return w; }
; __device__ __forceinline__ float fexp2(float x) { return __builtin_amdgcn_exp2f(x); }
; __device__ __forceinline__ float silu_f(float z) { return z * __builtin_amdgcn_rcpf(1.0f + fexp2(-LOG2E * z)); }
; __device__ __forceinline__ void bcombine_phase(const bf16_t* H, const float* MD, bf16_t* YZ, int Tc) {
;     const int lane = otid() & 63; const int gw = (obid() * NTHREADS + otid()) >> 6, nw = (gridDim.x * NTHREADS) >> 6;
;     const int h = lane >> 3, d0 = (lane & 7) * 8;
;     for (int row = gw; row < Tc; row += nw) {
;         float mm[3], dd[3];
; #pragma unroll
;         for (int g = 0; g < 3; ++g) { mm[g] = MD[((size_t)row * 24 + g * 8 + h) * 2]; dd[g] = MD[((size_t)row * 24 + g * 8 + h) * 2 + 1]; }
;         const float M = fmaxf(mm[0], fmaxf(mm[1], mm[2]));
;         float w[3]; float ws = 0.f;
; #pragma unroll
;         for (int g = 0; g < 3; ++g) { w[g] = dd[g] * fexp2(mm[g] - M); ws += w[g]; }
;         const float inv = 1.0f / ws;
;         float acc[8];
; #pragma unroll
;         for (int i = 0; i < 8; ++i) acc[i] = 0.f;
; #pragma unroll
;         for (int g = 0; g < 3; ++g) { const u32x4 ow = *(const u32x4*)(H + (size_t)row * NP1 + BQ + g * 512 + h * 64 + d0); float f[8]; unpack8(ow, f);
; #pragma unroll
;             for (int i = 0; i < 8; ++i) acc[i] += w[g] * inv * f[i]; }
;         const u32x4 zw = *(const u32x4*)(H + (size_t)row * NP1 + BZ + h * 64 + d0); float zf[8]; unpack8(zw, zf);
; #pragma unroll
;         for (int i = 0; i < 8; ++i) acc[i] *= silu_f(zf[i]);
;         *(u32x4*)(YZ + (size_t)row * 2048 + 512 + h * 64 + d0) = pack8(acc);
;     }
; }
.LBB0_708:
	v_lshl_add_u64 v[2:3], s[92:93], 0, v[12:13]
	global_load_dwordx2 v[18:19], v[2:3], off offset:-68
	global_load_dwordx2 v[20:21], v[2:3], off offset:-4
	global_load_dwordx2 v[22:23], v[2:3], off offset:60
	v_lshl_add_u64 v[26:27], s[92:93], 0, v[10:11]
	s_mov_b32 s12, 0xc8cb000
	v_add_co_u32_e32 v28, vcc, s12, v26
	v_add_u32_e32 v6, s25, v6
	s_nop 0
	v_addc_co_u32_e32 v29, vcc, 0, v27, vcc
	s_mov_b32 s12, 0xc8cd000
	v_add_co_u32_e32 v34, vcc, s12, v26
	s_nop 1
	v_addc_co_u32_e32 v35, vcc, 0, v27, vcc
	global_load_dwordx4 v[36:39], v[28:29], off offset:896
	global_load_dwordx4 v[40:43], v[28:29], off offset:1920
	global_load_dwordx4 v[44:47], v[34:35], off offset:1920
	global_load_dwordx4 v[48:51], v[28:29], off offset:2944
	v_lshl_add_u64 v[10:11], v[10:11], 0, s[18:19]
	v_lshl_add_u64 v[12:13], v[12:13], 0, s[20:21]
	s_waitcnt vmcnt(4)
	v_max3_f32 v0, v18, v20, v22
	v_sub_f32_e32 v2, v18, v0
	v_exp_f32_e32 v25, v2
	v_sub_f32_e32 v2, v20, v0
	v_exp_f32_e32 v24, v2
	v_sub_f32_e32 v0, v22, v0
	v_exp_f32_e32 v0, v0
	v_mov_b32_e32 v18, v21
	v_pk_mul_f32 v[18:19], v[18:19], v[24:25]
	v_mul_f32_e32 v7, v23, v0
	v_add_f32_e32 v20, 0, v19
	v_add_f32_e32 v20, v18, v20
	v_fmac_f32_e32 v20, v23, v0
	v_div_scale_f32 v0, s[12:13], v20, v20, 1.0
	v_rcp_f32_e32 v21, v0
	s_mov_b32 s12, 0xc8cd000
	v_fma_f32 v22, -v0, v21, 1.0
	v_fmac_f32_e32 v21, v22, v21
	v_div_scale_f32 v22, vcc, 1.0, v20, 1.0
	v_mul_f32_e32 v23, v22, v21
	v_fma_f32 v24, -v0, v23, v22
	v_fmac_f32_e32 v23, v24, v21
	v_fma_f32 v0, -v0, v23, v22
	v_div_fmas_f32 v0, v0, v21, v23
	v_div_fixup_f32 v0, v0, v20, 1.0
	v_pk_mul_f32 v[18:19], v[18:19], v[0:1] op_sel_hi:[1,0]
	s_waitcnt vmcnt(3)
	v_mov_b64_e32 v[2:3], v[36:37]
	v_mov_b64_e32 v[4:5], v[38:39]
	v_lshlrev_b32_e32 v23, 16, v2
	s_waitcnt vmcnt(2)
	v_mov_b64_e32 v[14:15], v[40:41]
	v_mov_b64_e32 v[16:17], v[42:43]
	v_lshlrev_b32_e32 v22, 16, v14
	v_pk_mul_f32 v[22:23], v[18:19], v[22:23]
	v_lshlrev_b32_e32 v21, 16, v5
	v_add_f32_e32 v23, 0, v23
	v_add_f32_e32 v24, v22, v23
	v_and_b32_e32 v23, 0xffff0000, v2
	v_and_b32_e32 v22, 0xffff0000, v14
	v_pk_mul_f32 v[22:23], v[18:19], v[22:23]
	v_add_co_u32_e32 v14, vcc, s12, v26
	v_add_f32_e32 v2, 0, v23
	v_add_f32_e32 v25, v22, v2
	v_lshlrev_b32_e32 v23, 16, v3
	v_lshlrev_b32_e32 v22, 16, v15
	v_pk_mul_f32 v[22:23], v[18:19], v[22:23]
	v_and_b32_e32 v3, 0xffff0000, v3
	v_add_f32_e32 v2, 0, v23
	v_add_f32_e32 v22, v22, v2
	v_and_b32_e32 v2, 0xffff0000, v15
	v_pk_mul_f32 v[2:3], v[18:19], v[2:3]
	v_addc_co_u32_e32 v15, vcc, 0, v27, vcc
	v_add_f32_e32 v3, 0, v3
	v_add_f32_e32 v23, v2, v3
	v_lshlrev_b32_e32 v3, 16, v4
	v_lshlrev_b32_e32 v2, 16, v16
	v_pk_mul_f32 v[2:3], v[18:19], v[2:3]
	v_lshlrev_b32_e32 v20, 16, v17
	v_add_f32_e32 v3, 0, v3
	v_add_f32_e32 v30, v2, v3
	v_and_b32_e32 v3, 0xffff0000, v4
	v_and_b32_e32 v2, 0xffff0000, v16
	v_pk_mul_f32 v[2:3], v[18:19], v[2:3]
	v_pk_mul_f32 v[20:21], v[18:19], v[20:21]
	v_add_f32_e32 v3, 0, v3
	v_add_f32_e32 v31, v2, v3
	v_and_b32_e32 v3, 0xffff0000, v5
	v_and_b32_e32 v2, 0xffff0000, v17
	v_pk_mul_f32 v[2:3], v[18:19], v[2:3]
	v_add_f32_e32 v3, 0, v3
	v_add_f32_e32 v33, v2, v3
	v_add_f32_e32 v21, 0, v21
	v_add_f32_e32 v32, v20, v21
	v_mul_f32_e32 v19, v7, v0
	v_cmp_le_i32_e32 vcc, s14, v6
	s_or_b64 s[30:31], vcc, s[30:31]
	s_waitcnt vmcnt(1)
	v_mov_b64_e32 v[14:15], v[44:45]
	v_mov_b64_e32 v[16:17], v[46:47]
	v_lshlrev_b32_e32 v20, 16, v14
	v_mul_f32_e32 v0, 0xbfb8aa3b, v20
	v_exp_f32_e32 v0, v0
	s_waitcnt vmcnt(0)
	v_mov_b64_e32 v[2:3], v[48:49]
	v_mov_b64_e32 v[4:5], v[50:51]
	v_lshlrev_b32_e32 v21, 16, v2
	v_add_f32_e32 v0, 1.0, v0
	v_rcp_f32_e32 v18, v0
	s_nop 0
	v_pk_mul_f32 v[20:21], v[18:19], v[20:21]
	s_nop 0
	v_add_f32_e32 v0, v21, v24
	v_mul_f32_e32 v0, v20, v0
	v_and_b32_e32 v20, 0xffff0000, v14
	v_and_b32_e32 v21, 0xffff0000, v2
	v_mul_f32_e32 v2, 0xbfb8aa3b, v20
	v_exp_f32_e32 v2, v2
	s_nop 0
	v_add_f32_e32 v2, 1.0, v2
	v_rcp_f32_e32 v18, v2
	s_nop 0
	v_pk_mul_f32 v[20:21], v[18:19], v[20:21]
	s_nop 0
	v_add_f32_e32 v2, v21, v25
	v_mul_f32_e32 v7, v20, v2
	v_lshlrev_b32_e32 v20, 16, v15
	v_mul_f32_e32 v2, 0xbfb8aa3b, v20
	v_exp_f32_e32 v2, v2
	v_lshlrev_b32_e32 v21, 16, v3
	v_and_b32_e32 v3, 0xffff0000, v3
	v_add_f32_e32 v2, 1.0, v2
	v_rcp_f32_e32 v18, v2
	s_nop 0
	v_pk_mul_f32 v[20:21], v[18:19], v[20:21]
	s_nop 0
	v_add_f32_e32 v2, v21, v22
	v_mul_f32_e32 v14, v20, v2
	v_and_b32_e32 v2, 0xffff0000, v15
	v_mul_f32_e32 v15, 0xbfb8aa3b, v2
	v_exp_f32_e32 v15, v15
	s_nop 0
	v_add_f32_e32 v15, 1.0, v15
	v_rcp_f32_e32 v18, v15
	s_nop 0
	v_pk_mul_f32 v[2:3], v[18:19], v[2:3]
	s_nop 0
	v_add_f32_e32 v3, v3, v23
	v_mul_f32_e32 v15, v2, v3
	v_lshlrev_b32_e32 v2, 16, v16
	v_mul_f32_e32 v18, 0xbfb8aa3b, v2
	v_exp_f32_e32 v18, v18
	v_lshlrev_b32_e32 v3, 16, v4
	v_add_f32_e32 v18, 1.0, v18
	v_rcp_f32_e32 v18, v18
	s_nop 0
	v_pk_mul_f32 v[2:3], v[18:19], v[2:3]
	s_nop 0
	v_add_f32_e32 v3, v3, v30
	v_mul_f32_e32 v20, v2, v3
	v_and_b32_e32 v2, 0xffff0000, v16
	v_and_b32_e32 v3, 0xffff0000, v4
	v_mul_f32_e32 v4, 0xbfb8aa3b, v2
	v_exp_f32_e32 v4, v4
	s_nop 0
	v_add_f32_e32 v4, 1.0, v4
	v_rcp_f32_e32 v18, v4
	s_nop 0
	v_pk_mul_f32 v[2:3], v[18:19], v[2:3]
	s_nop 0
	v_add_f32_e32 v3, v3, v31
	v_mul_f32_e32 v4, v2, v3
	v_lshlrev_b32_e32 v2, 16, v17
	v_mul_f32_e32 v16, 0xbfb8aa3b, v2
	v_exp_f32_e32 v16, v16
	v_lshlrev_b32_e32 v3, 16, v5
	v_add_f32_e32 v16, 1.0, v16
	v_rcp_f32_e32 v18, v16
	s_nop 0
	v_pk_mul_f32 v[2:3], v[18:19], v[2:3]
	s_nop 0
	v_add_f32_e32 v3, v3, v32
	v_mul_f32_e32 v16, v2, v3
	v_and_b32_e32 v2, 0xffff0000, v17
	v_and_b32_e32 v3, 0xffff0000, v5
	v_mul_f32_e32 v5, 0xbfb8aa3b, v2
	v_exp_f32_e32 v5, v5
	s_nop 0
	v_add_f32_e32 v5, 1.0, v5
	v_rcp_f32_e32 v18, v5
	s_nop 0
	v_pk_mul_f32 v[2:3], v[18:19], v[2:3]
	s_nop 0
	v_add_f32_e32 v3, v3, v33
	v_mul_f32_e32 v5, v2, v3
	v_cvt_pk_bf16_f32 v2, v0, v7
	v_cvt_pk_bf16_f32 v3, v14, v15
	v_lshl_add_u64 v[14:15], s[92:93], 0, v[8:9]
	v_lshl_add_u64 v[8:9], v[8:9], 0, s[16:17]
	v_cvt_pk_bf16_f32 v4, v20, v4
	v_cvt_pk_bf16_f32 v5, v16, v5
	global_store_dwordx4 v[14:15], v[2:5], off
	s_andn2_b64 exec, exec, s[30:31]
	s_cbranch_execnz .LBB0_708
